# phase-1 K loop: in the first K iteration of a tile the phase-4 wait only covers what was issued before the epilogue's 16 stores (vmcnt 24), the staged half needed in phase 7 gets its own counted wait;
# speedup vs baseline: 1.0239x; 1.0027x over previous
.LBB0_173:
	s_and_b32 s3, s0, 3
	s_mov_b64 s[0:1], 0x80
	s_add_i32 m0, s58, 0x18000
	v_lshl_add_u64 v[6:7], v[6:7], 0, s[0:1]
	s_ashr_i32 s63, s90, 31
	s_ashr_i32 s64, s16, 31
	s_lshl_b32 s6, s2, 13
	s_lshl_b32 s7, s3, 12
	s_waitcnt vmcnt(4)
	s_barrier
	global_load_lds_dwordx4 v[6:7], off
	v_lshl_add_u64 v[4:5], v[4:5], 0, s[0:1]
	s_add_i32 m0, s58, 0x1a000
	s_add_i32 s65, s58, 0x8000
	s_add_i32 s66, s58, 0xa000
	global_load_lds_dwordx4 v[4:5], off
	v_lshl_add_u64 v[2:3], v[2:3], 0, s[0:1]
	s_mov_b32 m0, s65
	s_add_u32 s4, s52, 0x10080
	global_load_lds_dwordx4 v[2:3], off
	v_lshl_add_u64 v[0:1], v[0:1], 0, s[0:1]
	s_mov_b32 m0, s66
	s_addc_u32 s5, s53, 0
	global_load_lds_dwordx4 v[0:1], off
	s_add_i32 m0, s58, 0x1c000
	v_lshl_add_u64 v[0:1], s[4:5], 0, v[130:131]
	global_load_lds_dwordx4 v[0:1], off
	v_lshl_add_u64 v[0:1], s[4:5], 0, v[134:135]
	s_add_i32 m0, s58, 0x1e000
	v_lshlrev_b32_e32 v3, 2, v8
	global_load_lds_dwordx4 v[0:1], off
	v_bfe_u32 v1, v8, 4, 2
	v_and_b32_e32 v0, 15, v8
	v_lshlrev_b32_e32 v2, 4, v1
	v_lshl_or_b32 v2, v0, 6, v2
	v_and_b32_e32 v3, 32, v3
	v_bitop3_b32 v4, v2, s6, v3 bitop3:0xde
	v_bitop3_b32 v158, v2, s7, v3 bitop3:0xde
	v_cmp_gt_u32_e64 s[6:7], 8, v0
	v_lshl_or_b32 v139, s2, 6, v0
	s_lshl_b32 s87, s3, 6
	v_cndmask_b32_e64 v0, 32, 0, s[6:7]
	v_lshl_or_b32 v138, v1, 3, v0
	v_lshlrev_b32_e32 v0, 14, v9
	v_and_b32_e32 v0, 0xffff8000, v0
	v_cmp_gt_u32_e64 s[2:3], 2, v1
	v_cmp_eq_u32_e64 s[4:5], 0, v1
	v_lshl_add_u32 v0, v10, 11, v0
	v_and_b32_e32 v1, 1, v9
	v_lshl_or_b32 v0, v1, 6, v0
	v_lshl_add_u32 v140, v11, 1, v0
	v_lshlrev_b32_e32 v0, 14, v12
	v_and_b32_e32 v0, 0xffff8000, v0
	v_lshl_add_u32 v0, v13, 11, v0
	v_and_b32_e32 v1, 1, v12
	s_waitcnt vmcnt(6)
	v_lshl_or_b32 v0, v1, 6, v0
	s_mov_b64 s[28:29], s[90:91]
	s_mov_b32 s67, s90
	v_lshl_add_u32 v142, v14, 1, v0
	s_add_i32 s89, 0, 0x10000
	s_add_i32 s90, 0, 0x14000
	s_movk_i32 s40, 0xe800
	v_mbcnt_lo_u32_b32 v0, -1, 0
	v_mov_b32_e32 v141, v137
	v_mov_b32_e32 v143, v137
	v_mov_b64_e32 v[144:145], 0xa00
	v_mov_b64_e32 v[146:147], 0x9ff
	s_movk_i32 s88, 0x141
	v_add_u32_e32 v159, s89, v158
	v_add_u32_e32 v160, 0, v4
	v_add_u32_e32 v161, s90, v158
	s_mov_b32 s41, -1
	v_mbcnt_hi_u32_b32 v162, -1, v0
	s_barrier
	s_mov_b32 s98, 0
	s_branch .LBB0_175
.LBB0_174:
	s_mov_b32 s98, 1
	s_and_b64 vcc, exec, s[8:9]
	s_mov_b32 s10, s42
	s_mov_b32 s12, s44
	s_mov_b64 s[52:53], s[48:49]
	s_mov_b64 s[50:51], s[46:47]
	s_cbranch_vccnz .LBB0_275

.LBB0_178:
	ds_read_b128 v[148:151], v159
	ds_read_b128 v[152:155], v159 offset:1024
	ds_read_b128 v[164:167], v159 offset:2048
	ds_read_b128 v[168:171], v159 offset:3072
	s_add_u32 s52, s50, 0xfffc0080
	s_addc_u32 s53, s51, -1
	s_cmp_eq_u32 s92, 12
	s_cselect_b32 s55, s11, s53
	s_cselect_b32 s54, s13, s52
	s_cselect_b32 s53, s17, s91
	s_cselect_b32 s52, s43, s45
	v_lshl_add_u64 v[156:157], s[50:51], 0, v[140:141]
	s_add_i32 m0, s58, 0xc000
	ds_read_b128 v[172:175], v160
	ds_read_b128 v[176:179], v160 offset:1024
	ds_read_b128 v[180:183], v160 offset:2048
	ds_read_b128 v[184:187], v160 offset:3072
	ds_read_b128 v[188:191], v160 offset:4096
	ds_read_b128 v[196:199], v160 offset:5120
	ds_read_b128 v[200:203], v160 offset:6144
	ds_read_b128 v[204:207], v160 offset:7168
	global_load_lds_dwordx4 v[156:157], off
	v_lshl_add_u64 v[156:157], s[50:51], 0, v[142:143]
	s_add_i32 m0, s58, 0xe000
	s_nop 0
	global_load_lds_dwordx4 v[156:157], off
	s_waitcnt lgkmcnt(8)
	s_barrier
	s_waitcnt lgkmcnt(0)
	s_setprio 1
	s_waitcnt lgkmcnt(0)
	v_mfma_f32_16x16x32_bf16 v[124:127], v[148:151], v[172:175], v[124:127]
	v_mfma_f32_16x16x32_bf16 v[120:123], v[164:167], v[172:175], v[120:123]
	v_mfma_f32_16x16x32_bf16 v[108:111], v[148:151], v[180:183], v[108:111]
	v_mfma_f32_16x16x32_bf16 v[104:107], v[164:167], v[180:183], v[104:107]
	v_mfma_f32_16x16x32_bf16 v[92:95], v[148:151], v[188:191], v[92:95]
	v_mfma_f32_16x16x32_bf16 v[88:91], v[164:167], v[188:191], v[88:91]
	v_mfma_f32_16x16x32_bf16 v[76:79], v[148:151], v[200:203], v[76:79]
	v_mfma_f32_16x16x32_bf16 v[72:75], v[164:167], v[200:203], v[72:75]
	v_mfma_f32_16x16x32_bf16 v[124:127], v[152:155], v[176:179], v[124:127]
	v_mfma_f32_16x16x32_bf16 v[120:123], v[168:171], v[176:179], v[120:123]
	v_mfma_f32_16x16x32_bf16 v[108:111], v[152:155], v[184:187], v[108:111]
	v_mfma_f32_16x16x32_bf16 v[104:107], v[168:171], v[184:187], v[104:107]
	v_mfma_f32_16x16x32_bf16 v[92:95], v[152:155], v[196:199], v[92:95]
	v_mfma_f32_16x16x32_bf16 v[88:91], v[168:171], v[196:199], v[88:91]
	v_mfma_f32_16x16x32_bf16 v[76:79], v[152:155], v[204:207], v[76:79]
	v_mfma_f32_16x16x32_bf16 v[72:75], v[168:171], v[204:207], v[72:75]
	s_setprio 0
	s_barrier
	s_add_i32 s93, s89, s57
	v_lshl_add_u64 v[156:157], s[52:53], 0, v[130:131]
	s_mov_b32 m0, s93
	ds_read_b128 v[208:211], v161
	ds_read_b128 v[212:215], v161 offset:1024
	ds_read_b128 v[216:219], v161 offset:2048
	ds_read_b128 v[220:223], v161 offset:3072
	global_load_lds_dwordx4 v[156:157], off
	v_lshl_add_u64 v[224:225], s[52:53], 0, v[134:135]
	s_add_i32 m0, s93, 0x2000
	s_nop 0
	global_load_lds_dwordx4 v[224:225], off
	s_barrier
	s_waitcnt lgkmcnt(0)
	s_setprio 1
	s_waitcnt lgkmcnt(0)
	v_mfma_f32_16x16x32_bf16 v[116:119], v[208:211], v[172:175], v[116:119]
	v_mfma_f32_16x16x32_bf16 v[112:115], v[216:219], v[172:175], v[112:115]
	v_mfma_f32_16x16x32_bf16 v[100:103], v[208:211], v[180:183], v[100:103]
	v_mfma_f32_16x16x32_bf16 v[96:99], v[216:219], v[180:183], v[96:99]
	v_mfma_f32_16x16x32_bf16 v[84:87], v[208:211], v[188:191], v[84:87]
	v_mfma_f32_16x16x32_bf16 v[80:83], v[216:219], v[188:191], v[80:83]
	v_mfma_f32_16x16x32_bf16 v[68:71], v[208:211], v[200:203], v[68:71]
	v_mfma_f32_16x16x32_bf16 v[64:67], v[216:219], v[200:203], v[64:67]
	v_mfma_f32_16x16x32_bf16 v[116:119], v[212:215], v[176:179], v[116:119]
	v_mfma_f32_16x16x32_bf16 v[112:115], v[220:223], v[176:179], v[112:115]
	v_mfma_f32_16x16x32_bf16 v[100:103], v[212:215], v[184:187], v[100:103]
	v_mfma_f32_16x16x32_bf16 v[96:99], v[220:223], v[184:187], v[96:99]
	v_mfma_f32_16x16x32_bf16 v[84:87], v[212:215], v[196:199], v[84:87]
	v_mfma_f32_16x16x32_bf16 v[80:83], v[220:223], v[196:199], v[80:83]
	v_mfma_f32_16x16x32_bf16 v[68:71], v[212:215], v[204:207], v[68:71]
	v_mfma_f32_16x16x32_bf16 v[64:67], v[220:223], v[204:207], v[64:67]
	s_setprio 0
	s_mov_b32 m0, s58
	v_lshl_add_u64 v[226:227], s[54:55], 0, v[128:129]
	s_barrier
	ds_read_b128 v[172:175], v160 offset:16384
	ds_read_b128 v[176:179], v160 offset:17408
	ds_read_b128 v[180:183], v160 offset:18432
	ds_read_b128 v[184:187], v160 offset:19456
	ds_read_b128 v[188:191], v160 offset:20480
	ds_read_b128 v[196:199], v160 offset:21504
	ds_read_b128 v[200:203], v160 offset:22528
	ds_read_b128 v[204:207], v160 offset:23552
	global_load_lds_dwordx4 v[226:227], off
	v_lshl_add_u64 v[228:229], s[54:55], 0, v[132:133]
	s_mov_b32 m0, s59
	s_nop 0
	global_load_lds_dwordx4 v[228:229], off
	s_barrier
	s_waitcnt lgkmcnt(0)
	s_setprio 1
	s_waitcnt lgkmcnt(0)
	v_mfma_f32_16x16x32_bf16 v[60:63], v[148:151], v[172:175], v[60:63]
	v_mfma_f32_16x16x32_bf16 v[56:59], v[164:167], v[172:175], v[56:59]
	v_mfma_f32_16x16x32_bf16 v[44:47], v[148:151], v[180:183], v[44:47]
	v_mfma_f32_16x16x32_bf16 v[40:43], v[164:167], v[180:183], v[40:43]
	v_mfma_f32_16x16x32_bf16 v[28:31], v[148:151], v[188:191], v[28:31]
	v_mfma_f32_16x16x32_bf16 v[24:27], v[164:167], v[188:191], v[24:27]
	v_mfma_f32_16x16x32_bf16 v[12:15], v[148:151], v[200:203], v[12:15]
	v_mfma_f32_16x16x32_bf16 v[8:11], v[164:167], v[200:203], v[8:11]
	v_mfma_f32_16x16x32_bf16 v[60:63], v[152:155], v[176:179], v[60:63]
	v_mfma_f32_16x16x32_bf16 v[56:59], v[168:171], v[176:179], v[56:59]
	v_mfma_f32_16x16x32_bf16 v[44:47], v[152:155], v[184:187], v[44:47]
	v_mfma_f32_16x16x32_bf16 v[40:43], v[168:171], v[184:187], v[40:43]
	v_mfma_f32_16x16x32_bf16 v[28:31], v[152:155], v[196:199], v[28:31]
	v_mfma_f32_16x16x32_bf16 v[24:27], v[168:171], v[196:199], v[24:27]
	v_mfma_f32_16x16x32_bf16 v[12:15], v[152:155], v[204:207], v[12:15]
	v_mfma_f32_16x16x32_bf16 v[8:11], v[168:171], v[204:207], v[8:11]
	s_setprio 0
	s_barrier
	s_add_u32 s94, s52, 0x10000
	s_addc_u32 s95, s53, 0
	s_add_i32 s93, s90, s57
	v_lshl_add_u64 v[148:149], s[94:95], 0, v[130:131]
	s_mov_b32 m0, s93
	s_nop 0
	global_load_lds_dwordx4 v[148:149], off
	v_lshl_add_u64 v[148:149], s[94:95], 0, v[134:135]
	s_add_i32 m0, s93, 0x2000
	s_nop 0
	global_load_lds_dwordx4 v[148:149], off
	s_cmp_eq_u32 s98, 0
	s_cbranch_scc1 .Lk1_w4n
	s_mov_b32 s98, 0
	s_waitcnt vmcnt(24)
	s_branch .Lk1_w4j
.Lk1_w4n:
	s_waitcnt vmcnt(6)
.Lk1_w4j:
	s_barrier
	s_setprio 1
	v_mfma_f32_16x16x32_bf16 v[52:55], v[208:211], v[172:175], v[52:55]
	v_mfma_f32_16x16x32_bf16 v[48:51], v[216:219], v[172:175], v[48:51]
	v_mfma_f32_16x16x32_bf16 v[36:39], v[208:211], v[180:183], v[36:39]
	v_mfma_f32_16x16x32_bf16 v[32:35], v[216:219], v[180:183], v[32:35]
	v_mfma_f32_16x16x32_bf16 v[20:23], v[208:211], v[188:191], v[20:23]
	v_mfma_f32_16x16x32_bf16 v[16:19], v[216:219], v[188:191], v[16:19]
	v_mfma_f32_16x16x32_bf16 v[4:7], v[208:211], v[200:203], v[4:7]
	v_mfma_f32_16x16x32_bf16 v[0:3], v[216:219], v[200:203], v[0:3]
	v_mfma_f32_16x16x32_bf16 v[52:55], v[212:215], v[176:179], v[52:55]
	v_mfma_f32_16x16x32_bf16 v[48:51], v[220:223], v[176:179], v[48:51]
	v_mfma_f32_16x16x32_bf16 v[36:39], v[212:215], v[184:187], v[36:39]
	v_mfma_f32_16x16x32_bf16 v[32:35], v[220:223], v[184:187], v[32:35]
	v_mfma_f32_16x16x32_bf16 v[20:23], v[212:215], v[196:199], v[20:23]
	v_mfma_f32_16x16x32_bf16 v[16:19], v[220:223], v[196:199], v[16:19]
	v_mfma_f32_16x16x32_bf16 v[4:7], v[212:215], v[204:207], v[4:7]
	v_mfma_f32_16x16x32_bf16 v[0:3], v[220:223], v[204:207], v[0:3]
	s_setprio 0
	s_add_i32 s93, 0, 0x18000
	v_add_u32_e32 v136, s93, v158
	s_barrier
	ds_read_b128 v[148:151], v136
	ds_read_b128 v[152:155], v136 offset:1024
	ds_read_b128 v[164:167], v136 offset:2048
	ds_read_b128 v[168:171], v136 offset:3072
	s_add_u32 s54, s54, 0x40000
	s_addc_u32 s55, s55, 0
	s_mov_b32 m0, s60
	v_lshl_add_u64 v[208:209], s[54:55], 0, v[128:129]
	ds_read_b128 v[172:175], v160 offset:32768
	ds_read_b128 v[176:179], v160 offset:33792
	ds_read_b128 v[180:183], v160 offset:34816
	ds_read_b128 v[184:187], v160 offset:35840
	ds_read_b128 v[188:191], v160 offset:36864
	ds_read_b128 v[196:199], v160 offset:37888
	ds_read_b128 v[200:203], v160 offset:38912
	ds_read_b128 v[204:207], v160 offset:39936
	global_load_lds_dwordx4 v[208:209], off
	v_lshl_add_u64 v[208:209], s[54:55], 0, v[132:133]
	s_mov_b32 m0, s61
	s_nop 0
	global_load_lds_dwordx4 v[208:209], off
	s_waitcnt lgkmcnt(8)
	s_barrier
	s_waitcnt lgkmcnt(0)
	s_setprio 1
	s_waitcnt lgkmcnt(0)
	v_mfma_f32_16x16x32_bf16 v[124:127], v[148:151], v[172:175], v[124:127]
	v_mfma_f32_16x16x32_bf16 v[120:123], v[164:167], v[172:175], v[120:123]
	v_mfma_f32_16x16x32_bf16 v[108:111], v[148:151], v[180:183], v[108:111]
	v_mfma_f32_16x16x32_bf16 v[104:107], v[164:167], v[180:183], v[104:107]
	v_mfma_f32_16x16x32_bf16 v[92:95], v[148:151], v[188:191], v[92:95]
	v_mfma_f32_16x16x32_bf16 v[88:91], v[164:167], v[188:191], v[88:91]
	v_mfma_f32_16x16x32_bf16 v[76:79], v[148:151], v[200:203], v[76:79]
	v_mfma_f32_16x16x32_bf16 v[72:75], v[164:167], v[200:203], v[72:75]
	v_mfma_f32_16x16x32_bf16 v[124:127], v[152:155], v[176:179], v[124:127]
	v_mfma_f32_16x16x32_bf16 v[120:123], v[168:171], v[176:179], v[120:123]
	v_mfma_f32_16x16x32_bf16 v[108:111], v[152:155], v[184:187], v[108:111]
	v_mfma_f32_16x16x32_bf16 v[104:107], v[168:171], v[184:187], v[104:107]
	v_mfma_f32_16x16x32_bf16 v[92:95], v[152:155], v[196:199], v[92:95]
	v_mfma_f32_16x16x32_bf16 v[88:91], v[168:171], v[196:199], v[88:91]
	v_mfma_f32_16x16x32_bf16 v[76:79], v[152:155], v[204:207], v[76:79]
	v_mfma_f32_16x16x32_bf16 v[72:75], v[168:171], v[204:207], v[72:75]
	s_setprio 0
	s_barrier
	s_add_i32 s54, 0, 0x1c000
	s_add_i32 s55, s93, s57
	v_add_u32_e32 v136, s54, v158
	v_lshl_add_u64 v[156:157], v[156:157], 0, s[0:1]
	s_mov_b32 m0, s55
	ds_read_b128 v[208:211], v136
	ds_read_b128 v[212:215], v136 offset:1024
	ds_read_b128 v[216:219], v136 offset:2048
	ds_read_b128 v[220:223], v136 offset:3072
	global_load_lds_dwordx4 v[156:157], off
	v_lshl_add_u64 v[156:157], v[224:225], 0, s[0:1]
	s_add_i32 m0, s55, 0x2000
	s_nop 0
	global_load_lds_dwordx4 v[156:157], off
	s_barrier
	s_waitcnt lgkmcnt(0)
	s_setprio 1
	s_waitcnt lgkmcnt(0)
	v_mfma_f32_16x16x32_bf16 v[116:119], v[208:211], v[172:175], v[116:119]
	v_mfma_f32_16x16x32_bf16 v[112:115], v[216:219], v[172:175], v[112:115]
	v_mfma_f32_16x16x32_bf16 v[100:103], v[208:211], v[180:183], v[100:103]
	v_mfma_f32_16x16x32_bf16 v[96:99], v[216:219], v[180:183], v[96:99]
	v_mfma_f32_16x16x32_bf16 v[84:87], v[208:211], v[188:191], v[84:87]
	v_mfma_f32_16x16x32_bf16 v[80:83], v[216:219], v[188:191], v[80:83]
	v_mfma_f32_16x16x32_bf16 v[68:71], v[208:211], v[200:203], v[68:71]
	v_mfma_f32_16x16x32_bf16 v[64:67], v[216:219], v[200:203], v[64:67]
	v_mfma_f32_16x16x32_bf16 v[116:119], v[212:215], v[176:179], v[116:119]
	v_mfma_f32_16x16x32_bf16 v[112:115], v[220:223], v[176:179], v[112:115]
	v_mfma_f32_16x16x32_bf16 v[100:103], v[212:215], v[184:187], v[100:103]
	v_mfma_f32_16x16x32_bf16 v[96:99], v[220:223], v[184:187], v[96:99]
	v_mfma_f32_16x16x32_bf16 v[84:87], v[212:215], v[196:199], v[84:87]
	v_mfma_f32_16x16x32_bf16 v[80:83], v[220:223], v[196:199], v[80:83]
	v_mfma_f32_16x16x32_bf16 v[68:71], v[212:215], v[204:207], v[68:71]
	v_mfma_f32_16x16x32_bf16 v[64:67], v[220:223], v[204:207], v[64:67]
	s_setprio 0
	s_mov_b32 m0, s65
	v_lshl_add_u64 v[156:157], v[226:227], 0, s[0:1]
	s_waitcnt vmcnt(10)
	s_barrier
	ds_read_b128 v[172:175], v160 offset:49152
	ds_read_b128 v[176:179], v160 offset:50176
	ds_read_b128 v[180:183], v160 offset:51200
	ds_read_b128 v[184:187], v160 offset:52224
	ds_read_b128 v[188:191], v160 offset:53248
	ds_read_b128 v[196:199], v160 offset:54272
	ds_read_b128 v[200:203], v160 offset:55296
	ds_read_b128 v[204:207], v160 offset:56320
	global_load_lds_dwordx4 v[156:157], off
	v_lshl_add_u64 v[156:157], v[228:229], 0, s[0:1]
	s_mov_b32 m0, s66
	s_nop 0
	global_load_lds_dwordx4 v[156:157], off
	s_barrier
	s_waitcnt lgkmcnt(0)
	s_setprio 1
	s_waitcnt lgkmcnt(0)
	v_mfma_f32_16x16x32_bf16 v[60:63], v[148:151], v[172:175], v[60:63]
	v_mfma_f32_16x16x32_bf16 v[56:59], v[164:167], v[172:175], v[56:59]
	v_mfma_f32_16x16x32_bf16 v[44:47], v[148:151], v[180:183], v[44:47]
	v_mfma_f32_16x16x32_bf16 v[40:43], v[164:167], v[180:183], v[40:43]
	v_mfma_f32_16x16x32_bf16 v[28:31], v[148:151], v[188:191], v[28:31]
	v_mfma_f32_16x16x32_bf16 v[24:27], v[164:167], v[188:191], v[24:27]
	v_mfma_f32_16x16x32_bf16 v[12:15], v[148:151], v[200:203], v[12:15]
	v_mfma_f32_16x16x32_bf16 v[8:11], v[164:167], v[200:203], v[8:11]
	v_mfma_f32_16x16x32_bf16 v[60:63], v[152:155], v[176:179], v[60:63]
	v_mfma_f32_16x16x32_bf16 v[56:59], v[168:171], v[176:179], v[56:59]
	v_mfma_f32_16x16x32_bf16 v[44:47], v[152:155], v[184:187], v[44:47]
	v_mfma_f32_16x16x32_bf16 v[40:43], v[168:171], v[184:187], v[40:43]
	v_mfma_f32_16x16x32_bf16 v[28:31], v[152:155], v[196:199], v[28:31]
	v_mfma_f32_16x16x32_bf16 v[24:27], v[168:171], v[196:199], v[24:27]
	v_mfma_f32_16x16x32_bf16 v[12:15], v[152:155], v[204:207], v[12:15]
	v_mfma_f32_16x16x32_bf16 v[8:11], v[168:171], v[204:207], v[8:11]
	s_setprio 0
	s_barrier
	s_add_u32 s52, s52, 0x10080
	s_addc_u32 s53, s53, 0
	s_add_i32 s54, s54, s57
	v_lshl_add_u64 v[148:149], s[52:53], 0, v[130:131]
	s_mov_b32 m0, s54
	s_nop 0
	global_load_lds_dwordx4 v[148:149], off
	v_lshl_add_u64 v[148:149], s[52:53], 0, v[134:135]
	s_add_i32 m0, s54, 0x2000
	s_nop 0
	global_load_lds_dwordx4 v[148:149], off
	s_waitcnt vmcnt(6)
	s_barrier
	s_setprio 1
	v_mfma_f32_16x16x32_bf16 v[52:55], v[208:211], v[172:175], v[52:55]
	v_mfma_f32_16x16x32_bf16 v[48:51], v[216:219], v[172:175], v[48:51]
	v_mfma_f32_16x16x32_bf16 v[36:39], v[208:211], v[180:183], v[36:39]
	v_mfma_f32_16x16x32_bf16 v[32:35], v[216:219], v[180:183], v[32:35]
	v_mfma_f32_16x16x32_bf16 v[20:23], v[208:211], v[188:191], v[20:23]
	v_mfma_f32_16x16x32_bf16 v[16:19], v[216:219], v[188:191], v[16:19]
	v_mfma_f32_16x16x32_bf16 v[4:7], v[208:211], v[200:203], v[4:7]
	v_mfma_f32_16x16x32_bf16 v[0:3], v[216:219], v[200:203], v[0:3]
	v_mfma_f32_16x16x32_bf16 v[52:55], v[212:215], v[176:179], v[52:55]
	v_mfma_f32_16x16x32_bf16 v[48:51], v[220:223], v[176:179], v[48:51]
	v_mfma_f32_16x16x32_bf16 v[36:39], v[212:215], v[184:187], v[36:39]
	v_mfma_f32_16x16x32_bf16 v[32:35], v[220:223], v[184:187], v[32:35]
	v_mfma_f32_16x16x32_bf16 v[20:23], v[212:215], v[196:199], v[20:23]
	v_mfma_f32_16x16x32_bf16 v[16:19], v[220:223], v[196:199], v[16:19]
	v_mfma_f32_16x16x32_bf16 v[4:7], v[212:215], v[204:207], v[4:7]
	v_mfma_f32_16x16x32_bf16 v[0:3], v[220:223], v[204:207], v[0:3]
	s_setprio 0
	s_add_i32 s92, s92, 2
	s_add_u32 s50, s50, 0x100
	s_addc_u32 s51, s51, 0
	s_add_u32 s45, s45, 0x100
	s_addc_u32 s91, s91, 0
	s_cmp_gt_u32 s92, 13
	s_barrier
	s_cbranch_scc0 .LBB0_178
	v_lshl_add_u32 v148, s12, 8, v139
	v_and_b32_e32 v149, 24, v138
	s_lshl_b32 s11, s10, 8
	s_or_b32 s11, s11, s87
	s_cmp_gt_i32 s10, 11
	s_cbranch_scc1 .Le1_gates
	s_lshr_b32 s13, s10, 1
	s_lshl_b32 s50, s13, 25
	s_add_u32 s50, s20, s50
	s_addc_u32 s51, s21, 0
	s_bfe_u32 s17, s11, 0x30006
	v_ashrrev_i32_e32 v150, 8, v148
	v_and_or_b32 v150, v150, -8, s17
	v_mov_b32_e32 v151, 0
	v_lshlrev_b64 v[150:151], 18, v[150:151]
	v_lshlrev_b32_e32 v136, 7, v148
	v_and_b32_e32 v136, 0x3ff80, v136
	v_lshl_add_u32 v136, v149, 1, v136
	v_lshl_add_u64 v[150:151], v[150:151], 0, v[136:137]
	v_lshl_add_u64 v[150:151], v[150:151], 0, s[50:51]
	s_movk_i32 s11, 0x800
	s_movk_i32 s17, 0x2800
	s_branch .Le1_addr
